# asel: XCD-local unit map (all KV blocks of one (b,h) on one XCD) so gathered Q rows are shared in L2
# speedup vs baseline: 1.1235x; 1.0097x over previous
.LBB0_1247:
	s_mul_hi_i32 s0, s71, 0x84210843
	s_add_i32 s0, s0, s71
	s_lshr_b32 s1, s0, 31
	s_ashr_i32 s0, s0, 10
	s_add_i32 s1, s0, s1
	s_mul_i32 s0, s1, 0xfffff840
	s_add_i32 s34, s0, s71
	s_and_b32 s0, s34, 7
	s_mulk_i32 s0, 0xf8
	s_bfe_u32 s4, s34, 0x30003
	s_mulk_i32 s4, 31
	s_add_i32 s0, s0, s4
	s_lshr_b32 s4, s34, 6
	s_add_i32 s34, s0, s4
	s_mul_hi_i32 s0, s34, 0x84210843
	s_add_i32 s0, s0, s34
	s_lshr_b32 s4, s0, 31
	s_ashr_i32 s0, s0, 4
	s_add_i32 s0, s0, s4
	s_mul_i32 s14, s0, 0xffffffe1
	s_add_i32 s14, s14, s34
	s_lshl_b32 s4, s14, 8
	s_lshl_b32 s15, s1, 10
	s_sub_i32 s5, 0x1f00, s4
	s_cmp_ge_i32 s15, s5
	s_cbranch_scc1 .LBB0_1246
	s_ashr_i32 s35, s34, 31
	s_lshl_b32 s11, s1, 3
	s_lshl_b64 s[34:35], s[34:35], 2
	s_add_u32 s34, s16, s34
	s_addc_u32 s35, s17, s35
	global_load_dword v110, v101, s[34:35]
	s_waitcnt vmcnt(0)
	v_readfirstlane_b32 s1, v110
	s_addk_i32 s1, 0x7f
	s_ashr_i32 s10, s1, 7
	s_cmp_ge_i32 s11, s10
	s_cbranch_scc1 .LBB0_1246
	s_ashr_i32 s1, s0, 31
	s_lshl_b64 s[38:39], s[0:1], 13
	s_ashr_i32 s5, s4, 31
	s_add_u32 s34, s38, s4
	s_addc_u32 s35, s39, s5
	s_lshl_b64 s[34:35], s[34:35], 7
	s_add_u32 s34, s26, s34
	s_addc_u32 s35, s27, s35
	s_lshl_b64 s[36:37], s[0:1], 20
	v_mov_b32_e32 v82, v196
	s_barrier
	s_add_u32 s33, s46, s36
	s_addc_u32 s36, s47, s37
	v_ashrrev_i32_e32 v64, 3, v82
	s_lshl_b64 s[4:5], s[4:5], 1
	v_lshlrev_b32_e32 v32, 4, v82
	v_add_u32_e32 v66, 32, v64
	s_add_u32 s4, s33, s4
	v_and_b32_e32 v100, 0x70, v32
	v_ashrrev_i32_e32 v65, 31, v64
	v_ashrrev_i32_e32 v67, 31, v66
	v_ashrrev_i32_e32 v80, 5, v82
	s_addc_u32 s5, s36, s5
	v_lshl_add_u64 v[24:25], s[34:35], 0, v[100:101]
	v_lshlrev_b64 v[0:1], 7, v[64:65]
	v_lshlrev_b64 v[2:3], 7, v[66:67]
	v_add_u32_e32 v68, 64, v64
	v_add_u32_e32 v70, 0x60, v64
	v_and_b32_e32 v100, 0x1f0, v32
	v_ashrrev_i32_e32 v81, 31, v80
	v_lshl_add_u64 v[0:1], v[24:25], 0, v[0:1]
	v_lshl_add_u64 v[4:5], v[24:25], 0, v[2:3]
	v_ashrrev_i32_e32 v69, 31, v68
	v_ashrrev_i32_e32 v71, 31, v70
	v_lshl_add_u64 v[32:33], s[4:5], 0, v[100:101]
	s_waitcnt lgkmcnt(0)
	v_lshlrev_b64 v[34:35], 14, v[80:81]
	global_load_dwordx4 v[0:3], v[0:1], off
	s_nop 0
	global_load_dwordx4 v[4:7], v[4:5], off
	v_lshlrev_b64 v[8:9], 7, v[68:69]
	v_lshlrev_b64 v[10:11], 7, v[70:71]
	v_add_u32_e32 v72, 0x80, v64
	v_add_u32_e32 v74, 0xa0, v64
	v_lshl_add_u64 v[60:61], v[32:33], 0, v[34:35]
	v_lshl_add_u64 v[8:9], v[24:25], 0, v[8:9]
	v_lshl_add_u64 v[12:13], v[24:25], 0, v[10:11]
	v_ashrrev_i32_e32 v73, 31, v72
	v_ashrrev_i32_e32 v75, 31, v74
	v_add_co_u32_e32 v36, vcc, s62, v60
	global_load_dwordx4 v[8:11], v[8:9], off
	s_nop 0
	global_load_dwordx4 v[12:15], v[12:13], off
	v_lshlrev_b64 v[16:17], 7, v[72:73]
	v_lshlrev_b64 v[18:19], 7, v[74:75]
	v_add_u32_e32 v76, 0xc0, v64
	v_add_u32_e32 v78, 0xe0, v64
	v_addc_co_u32_e32 v37, vcc, 0, v61, vcc
	v_lshl_add_u64 v[16:17], v[24:25], 0, v[16:17]
	v_lshl_add_u64 v[20:21], v[24:25], 0, v[18:19]
	v_ashrrev_i32_e32 v77, 31, v76
	v_ashrrev_i32_e32 v79, 31, v78
	v_add_co_u32_e32 v40, vcc, s63, v60
	global_load_dwordx4 v[16:19], v[16:17], off
	s_nop 0
	global_load_dwordx4 v[20:23], v[20:21], off
	v_lshlrev_b64 v[26:27], 7, v[76:77]
	v_lshlrev_b64 v[28:29], 7, v[78:79]
	v_addc_co_u32_e32 v41, vcc, 0, v61, vcc
	v_lshl_add_u64 v[26:27], v[24:25], 0, v[26:27]
	v_lshl_add_u64 v[28:29], v[24:25], 0, v[28:29]
	v_add_co_u32_e32 v44, vcc, s64, v60
	global_load_dwordx4 v[24:27], v[26:27], off
	s_nop 0
	global_load_dwordx4 v[28:31], v[28:29], off
	v_addc_co_u32_e32 v45, vcc, 0, v61, vcc
	v_add_co_u32_e32 v48, vcc, s65, v60
	global_load_dwordx4 v[32:35], v[60:61], off
	s_nop 0
	global_load_dwordx4 v[36:39], v[36:37], off
	v_addc_co_u32_e32 v49, vcc, 0, v61, vcc
	v_add_co_u32_e32 v52, vcc, s66, v60
	global_load_dwordx4 v[40:43], v[40:41], off
	s_nop 0
	global_load_dwordx4 v[44:47], v[44:45], off
	v_addc_co_u32_e32 v53, vcc, 0, v61, vcc
	v_add_co_u32_e32 v56, vcc, s67, v60
	global_load_dwordx4 v[48:51], v[48:49], off
	s_nop 0
	global_load_dwordx4 v[52:55], v[52:53], off
	v_addc_co_u32_e32 v57, vcc, 0, v61, vcc
	v_add_co_u32_e32 v60, vcc, s68, v60
	global_load_dwordx4 v[56:59], v[56:57], off
	s_nop 0
	v_addc_co_u32_e32 v61, vcc, 0, v61, vcc
	global_load_dwordx4 v[60:63], v[60:61], off
	v_lshrrev_b32_e32 v65, 1, v64
	v_xor_b32_e32 v65, v65, v82
	v_lshlrev_b32_e32 v65, 4, v65
	v_and_b32_e32 v65, 0x70, v65
	v_add_u32_e32 v65, 16, v65
	v_lshl_add_u32 v64, v64, 7, v65
	s_add_i32 s33, s11, 8
	s_mul_i32 s5, s0, 0x3e000
	s_mul_hi_i32 s4, s0, 0x3e000
	s_add_u32 s34, s28, s5
	s_addc_u32 s35, s29, s4
	s_not_b32 s4, s14
	s_lshl_b32 s4, s4, 7
	s_addk_i32 s4, 0x2000
	s_mul_i32 s4, s4, s14
	s_ashr_i32 s5, s4, 31
	s_lshl_b64 s[4:5], s[4:5], 1
	s_add_u32 s4, s34, s4
	s_addc_u32 s5, s35, s5
	s_or_b32 s34, s11, 1
	s_lshl_b32 s14, s34, 7
	s_waitcnt vmcnt(15)
	ds_write_b128 v64, v[0:3]
	v_lshl_add_u32 v0, v66, 7, v65
	s_waitcnt vmcnt(14)
	ds_write_b128 v0, v[4:7]
	v_lshl_add_u32 v0, v68, 7, v65
	s_min_i32 s10, s33, s10
	s_cmp_ge_i32 s34, s10
	s_cselect_b64 s[40:41], -1, 0
	s_and_b64 vcc, exec, s[40:41]
	s_waitcnt vmcnt(13)
	ds_write_b128 v0, v[8:11]
	v_lshl_add_u32 v0, v70, 7, v65
	s_waitcnt vmcnt(12)
	ds_write_b128 v0, v[12:15]
	v_lshl_add_u32 v0, v72, 7, v65
	v_add_u32_e32 v12, -1, v110
	v_add_u32_e32 v13, s15, v107
	v_add_u32_e32 v2, 0x100, v13
	v_add_u32_e32 v4, 0x180, v13
	v_add_u32_e32 v6, 0x200, v13
	v_add_u32_e32 v8, 0x280, v13
	v_add_u32_e32 v10, 0x300, v13
	v_min_i32_e32 v2, v2, v12
	v_min_i32_e32 v4, v4, v12
	s_waitcnt vmcnt(11)
	ds_write_b128 v0, v[16:19]
	v_lshl_add_u32 v0, v74, 7, v65
	s_waitcnt vmcnt(10)
	ds_write_b128 v0, v[20:23]
	v_lshl_add_u32 v0, v76, 7, v65
	v_min_i32_e32 v6, v6, v12
	v_min_i32_e32 v8, v8, v12
	v_min_i32_e32 v10, v10, v12
	v_ashrrev_i32_e32 v3, 31, v2
	v_ashrrev_i32_e32 v5, 31, v4
	s_waitcnt vmcnt(9)
	ds_write_b128 v0, v[24:27]
	v_lshl_add_u32 v0, v78, 7, v65
	s_waitcnt vmcnt(8)
	ds_write_b128 v0, v[28:31]
	v_mul_lo_u32 v0, v80, s60
	v_add3_u32 v0, 16, v100, v0
	v_add_u32_e32 v1, 0x8000, v0
	s_waitcnt vmcnt(7)
	ds_write2_b64 v1, v[32:33], v[34:35] offset1:1
	v_add_u32_e32 v1, 0x9040, v0
	s_waitcnt vmcnt(6)
	ds_write2_b64 v1, v[36:37], v[38:39] offset1:1
	v_add_u32_e32 v1, 0xa080, v0
	s_waitcnt vmcnt(5)
	ds_write2_b64 v1, v[40:41], v[42:43] offset1:1
	v_add_u32_e32 v1, 0xb0c0, v0
	s_waitcnt vmcnt(4)
	ds_write2_b64 v1, v[44:45], v[46:47] offset1:1
	v_add_u32_e32 v1, 0xc100, v0
	v_ashrrev_i32_e32 v7, 31, v6
	s_waitcnt vmcnt(3)
	ds_write2_b64 v1, v[48:49], v[50:51] offset1:1
	v_add_u32_e32 v1, 0xd140, v0
	s_waitcnt vmcnt(2)
	ds_write2_b64 v1, v[52:53], v[54:55] offset1:1
	v_add_u32_e32 v1, 0xe180, v0
	v_add_u32_e32 v0, 0xf1c0, v0
	v_ashrrev_i32_e32 v9, 31, v8
	s_waitcnt vmcnt(1)
	ds_write2_b64 v1, v[56:57], v[58:59] offset1:1
	v_ashrrev_i32_e32 v11, 31, v10
	v_lshl_add_u64 v[2:3], v[2:3], 1, s[4:5]
	s_waitcnt vmcnt(0)
	ds_write2_b64 v0, v[60:61], v[62:63] offset1:1
	v_min_i32_e32 v0, v13, v12
	v_ashrrev_i32_e32 v1, 31, v0
	v_lshl_add_u64 v[0:1], v[0:1], 1, s[4:5]
	s_waitcnt lgkmcnt(0)
	s_barrier
	global_load_ushort v100, v[0:1], off
	v_add_u32_e32 v0, s14, v107
	v_min_i32_e32 v0, v0, v12
	v_add_u32_e32 v13, 0x380, v13
	v_ashrrev_i32_e32 v1, 31, v0
	v_min_i32_e32 v12, v13, v12
	v_lshl_add_u64 v[0:1], v[0:1], 1, s[4:5]
	v_ashrrev_i32_e32 v13, 31, v12
	v_lshl_add_u64 v[4:5], v[4:5], 1, s[4:5]
	v_lshl_add_u64 v[6:7], v[6:7], 1, s[4:5]
	v_lshl_add_u64 v[8:9], v[8:9], 1, s[4:5]
	v_lshl_add_u64 v[10:11], v[10:11], 1, s[4:5]
	v_lshl_add_u64 v[12:13], v[12:13], 1, s[4:5]
	global_load_ushort v117, v[0:1], off
	global_load_ushort v116, v[2:3], off
	global_load_ushort v115, v[4:5], off
	global_load_ushort v114, v[6:7], off
	global_load_ushort v113, v[8:9], off
	global_load_ushort v112, v[10:11], off
	global_load_ushort v111, v[12:13], off
	v_mov_b32_e32 v1, s39
	s_waitcnt vmcnt(7)
	v_and_b32_e32 v118, 0x1fff, v100
	v_or_b32_e32 v0, s38, v118
	v_lshlrev_b64 v[0:1], 7, v[0:1]
	v_lshl_add_u64 v[0:1], v[102:103], 0, v[0:1]
	global_load_dwordx4 v[80:83], v[0:1], off offset:96
	global_load_dwordx4 v[84:87], v[0:1], off offset:64
	global_load_dwordx4 v[88:91], v[0:1], off offset:32
	global_load_dwordx4 v[92:95], v[0:1], off
	s_waitcnt vmcnt(3)
	v_mov_b64_e32 v[64:65], v[80:81]
	s_waitcnt vmcnt(2)
	v_mov_b64_e32 v[68:69], v[84:85]
	s_waitcnt vmcnt(1)
	v_mov_b64_e32 v[72:73], v[88:89]
	s_waitcnt vmcnt(0)
	v_mov_b64_e32 v[76:77], v[92:93]
	v_mov_b64_e32 v[66:67], v[82:83]
	v_mov_b64_e32 v[70:71], v[86:87]
	v_mov_b64_e32 v[74:75], v[90:91]
	v_mov_b64_e32 v[78:79], v[94:95]
	s_cbranch_vccnz .LBB0_1251
	v_and_b32_e32 v0, 0x1fff, v117
	v_or_b32_e32 v0, s38, v0
	v_mov_b32_e32 v1, s39
	v_lshlrev_b64 v[0:1], 7, v[0:1]
	v_lshl_add_u64 v[0:1], v[102:103], 0, v[0:1]
	global_load_dwordx4 v[76:79], v[0:1], off
	global_load_dwordx4 v[72:75], v[0:1], off offset:32
	global_load_dwordx4 v[68:71], v[0:1], off offset:64
	global_load_dwordx4 v[64:67], v[0:1], off offset:96
